# FoX softmax half trimmed: V source set-up moved into the MFMA half (after MFMA 0), no s_nop 3, first LDS reads of the next MFMA half hoisted 26 instructions into the softmax
# speedup vs baseline: 1.0094x; 1.0003x over previous
.Lfx_body:
	s_cmp_lt_u32 s62, 0x4000005e
	s_cselect_b64 s[78:79], -1, 0
	s_andn2_b64 vcc, exec, s[78:79]
	s_cbranch_vccnz .Lfx_h1_done
	s_andn2_b64 vcc, exec, s[80:81]
	s_cbranch_vccnz .Lfx_h1_qonly
	s_add_i32 s64, s77, s51
	v_add_u32_e32 v10, s64, v183
	v_add_u32_e32 v11, s64, v184
	v_add_u32_e32 v12, s64, v185
	v_add_u32_e32 v13, s64, v186
	s_add_i32 s65, s76, s51
	v_add_u32_e32 v14, s65, v174
	s_lshl_b32 s66, s50, 2
	s_add_i32 s66, s66, s76
	v_lshl_add_u32 v0, v144, 2, s66
	v_add_u32_e32 v0, 0x10000, v0
	s_waitcnt lgkmcnt(6)
	v_mfma_f32_32x32x16_bf16 v[64:79], v[2:5], v[196:199], v[64:79]
	ds_read_b64_tr_b16 v[220:221], v11 offset:32768
	ds_read_b64_tr_b16 v[222:223], v11 offset:34816
	s_lshl_b32 s64, s41, 7
	s_add_i32 s66, s64, 0xffffff80
	s_max_i32 s66, s66, 0
	s_mov_b32 s67, 0
	s_lshl_b64 s[28:29], s[66:67], 8
	s_add_u32 s28, s27, s28
	s_addc_u32 s29, s38, s29
	s_lshl_b64 s[68:69], s[66:67], 2
	s_add_u32 s68, s70, s68
	s_addc_u32 s69, s71, s69
	s_lshl_b64 s[30:31], s[66:67], 8
	s_add_u32 s30, s23, s30
	s_addc_u32 s31, s24, s31
	ds_read_b128 v[96:99], v0
	s_waitcnt lgkmcnt(7)
	v_mfma_f32_32x32x16_bf16 v[64:79], v[6:9], v[204:207], v[64:79]
	ds_read_b64_tr_b16 v[224:225], v11 offset:36864
	ds_read_b64_tr_b16 v[226:227], v11 offset:38912
	s_add_i32 s33, s73, s77
	s_mov_b32 m0, s33
	s_nop 0
	global_load_lds_dwordx4 v163, s[28:29]
	ds_read_b128 v[100:103], v0 offset:32
	s_waitcnt lgkmcnt(8)
	v_mfma_f32_32x32x16_bf16 v[64:79], v[212:215], v[200:203], v[64:79]
	ds_read_b64_tr_b16 v[228:229], v11 offset:40960
	ds_read_b64_tr_b16 v[230:231], v11 offset:43008
	ds_read_b128 v[80:83], v0 offset:128
	s_waitcnt lgkmcnt(9)
	v_mfma_f32_32x32x16_bf16 v[64:79], v[216:219], v[208:211], v[64:79]
	ds_read_b64_tr_b16 v[232:233], v11 offset:45056
	ds_read_b64_tr_b16 v[234:235], v11 offset:47104
	ds_read_b128 v[84:87], v0 offset:160
	s_waitcnt lgkmcnt(10)
	v_mfma_f32_32x32x16_bf16 v[48:63], v[220:223], v[196:199], v[48:63]
	ds_read_b64_tr_b16 v[2:3], v12 offset:32768
	ds_read_b64_tr_b16 v[4:5], v12 offset:34816
	s_add_i32 m0, s33, 0x400
	s_nop 0
	global_load_lds_dwordx4 v189, s[28:29]
	ds_read_b128 v[104:107], v0 offset:64
	s_waitcnt lgkmcnt(10)
	v_mfma_f32_32x32x16_bf16 v[48:63], v[224:227], v[204:207], v[48:63]
	ds_read_b64_tr_b16 v[6:7], v12 offset:36864
	ds_read_b64_tr_b16 v[8:9], v12 offset:38912
	ds_read_b128 v[108:111], v0 offset:96
	s_waitcnt lgkmcnt(10)
	v_mfma_f32_32x32x16_bf16 v[48:63], v[228:231], v[200:203], v[48:63]
	ds_read_b64_tr_b16 v[212:213], v12 offset:40960
	ds_read_b64_tr_b16 v[214:215], v12 offset:43008
	ds_read_b128 v[88:91], v0 offset:192
	s_waitcnt lgkmcnt(10)
	v_mfma_f32_32x32x16_bf16 v[48:63], v[232:235], v[208:211], v[48:63]
	ds_read_b64_tr_b16 v[216:217], v12 offset:45056
	ds_read_b64_tr_b16 v[218:219], v12 offset:47104
	s_add_i32 m0, s33, 0x800
	s_nop 0
	global_load_lds_dwordx4 v190, s[28:29]
	ds_read_b128 v[92:95], v0 offset:224
	s_waitcnt lgkmcnt(10)
	v_mfma_f32_32x32x16_bf16 v[32:47], v[2:5], v[196:199], v[32:47]
	ds_read_b64_tr_b16 v[220:221], v13 offset:32768
	ds_read_b64_tr_b16 v[222:223], v13 offset:34816
	s_waitcnt lgkmcnt(9)
	v_mfma_f32_32x32x16_bf16 v[32:47], v[6:9], v[204:207], v[32:47]
	ds_read_b64_tr_b16 v[224:225], v13 offset:36864
	ds_read_b64_tr_b16 v[226:227], v13 offset:38912
	s_waitcnt lgkmcnt(8)
	v_mfma_f32_32x32x16_bf16 v[32:47], v[212:215], v[200:203], v[32:47]
	ds_read_b64_tr_b16 v[228:229], v13 offset:40960
	ds_read_b64_tr_b16 v[230:231], v13 offset:43008
	s_add_i32 m0, s33, 0xc00
	s_nop 0
	global_load_lds_dwordx4 v191, s[28:29]
	s_waitcnt lgkmcnt(7)
	v_mfma_f32_32x32x16_bf16 v[32:47], v[216:219], v[208:211], v[32:47]
	ds_read_b64_tr_b16 v[232:233], v13 offset:45056
	ds_read_b64_tr_b16 v[234:235], v13 offset:47104
	s_waitcnt lgkmcnt(6)
	v_mfma_f32_32x32x16_bf16 v[16:31], v[220:223], v[196:199], v[16:31]
	v_add_u32_e32 v15, v14, v175
	ds_read_b128 v[2:5], v15
	s_waitcnt lgkmcnt(5)
	v_mfma_f32_32x32x16_bf16 v[16:31], v[224:227], v[204:207], v[16:31]
	ds_read_b128 v[6:9], v15 offset:8192
	s_add_i32 m0, s72, s77
	s_nop 0
	global_load_lds_dword v172, s[68:69]
	s_waitcnt lgkmcnt(4)
	v_mfma_f32_32x32x16_bf16 v[16:31], v[228:231], v[200:203], v[16:31]
	v_add_u32_e32 v15, v14, v176
	ds_read_b128 v[212:215], v15
	s_waitcnt lgkmcnt(3)
	v_mfma_f32_32x32x16_bf16 v[16:31], v[232:235], v[208:211], v[16:31]
	ds_read_b128 v[216:219], v15 offset:8192
	s_waitcnt lgkmcnt(3)
	v_mfma_f32_32x32x16_bf16 v[96:111], v[2:5], v[112:115], v[96:111]
	v_add_u32_e32 v15, v14, v177
	ds_read_b128 v[220:223], v15
	s_waitcnt lgkmcnt(3)
	v_mfma_f32_32x32x16_bf16 v[80:95], v[6:9], v[112:115], v[80:95]
	ds_read_b128 v[224:227], v15 offset:8192
	s_waitcnt lgkmcnt(3)
	v_mfma_f32_32x32x16_bf16 v[96:111], v[212:215], v[116:119], v[96:111]
	v_add_u32_e32 v15, v14, v178
	ds_read_b128 v[228:231], v15
	s_waitcnt lgkmcnt(3)
	v_mfma_f32_32x32x16_bf16 v[80:95], v[216:219], v[116:119], v[80:95]
	ds_read_b128 v[232:235], v15 offset:8192
	s_waitcnt lgkmcnt(3)
	v_mfma_f32_32x32x16_bf16 v[96:111], v[220:223], v[120:123], v[96:111]
	v_add_u32_e32 v15, v14, v179
	ds_read_b128 v[2:5], v15
	s_waitcnt lgkmcnt(3)
	v_mfma_f32_32x32x16_bf16 v[80:95], v[224:227], v[120:123], v[80:95]
	ds_read_b128 v[6:9], v15 offset:8192
	s_waitcnt lgkmcnt(3)
	v_mfma_f32_32x32x16_bf16 v[96:111], v[228:231], v[124:127], v[96:111]
	v_add_u32_e32 v15, v14, v180
	ds_read_b128 v[212:215], v15
	s_waitcnt lgkmcnt(3)
	v_mfma_f32_32x32x16_bf16 v[80:95], v[232:235], v[124:127], v[80:95]
	ds_read_b128 v[216:219], v15 offset:8192
	s_waitcnt lgkmcnt(3)
	v_mfma_f32_32x32x16_bf16 v[96:111], v[2:5], v[128:131], v[96:111]
	v_add_u32_e32 v15, v14, v181
	ds_read_b128 v[220:223], v15
	s_waitcnt lgkmcnt(3)
	v_mfma_f32_32x32x16_bf16 v[80:95], v[6:9], v[128:131], v[80:95]
	ds_read_b128 v[224:227], v15 offset:8192
	s_waitcnt lgkmcnt(3)
	v_mfma_f32_32x32x16_bf16 v[96:111], v[212:215], v[132:135], v[96:111]
	v_add_u32_e32 v15, v14, v182
	ds_read_b128 v[228:231], v15
	s_waitcnt lgkmcnt(3)
	v_mfma_f32_32x32x16_bf16 v[80:95], v[216:219], v[132:135], v[80:95]
	ds_read_b128 v[232:235], v15 offset:8192
	s_waitcnt lgkmcnt(0)
	s_waitcnt vmcnt(5)
	s_barrier
	v_mfma_f32_32x32x16_bf16 v[96:111], v[220:223], v[136:139], v[96:111]
	v_mfma_f32_32x32x16_bf16 v[80:95], v[224:227], v[136:139], v[80:95]
	v_mfma_f32_32x32x16_bf16 v[96:111], v[228:231], v[140:143], v[96:111]
	v_mfma_f32_32x32x16_bf16 v[80:95], v[232:235], v[140:143], v[80:95]
	s_nop 7
	s_branch .Lfx_h1_joined
.Lfx_h1_qonly:
	s_lshl_b32 s64, s41, 7
	s_add_i32 s66, s64, 0xffffff80
	s_max_i32 s66, s66, 0
	s_mov_b32 s67, 0
	s_lshl_b64 s[28:29], s[66:67], 8
	s_add_u32 s28, s27, s28
	s_addc_u32 s29, s38, s29
	s_lshl_b64 s[68:69], s[66:67], 2
	s_add_u32 s68, s70, s68
	s_addc_u32 s69, s71, s69
	s_lshl_b64 s[30:31], s[66:67], 8
	s_add_u32 s30, s23, s30
	s_addc_u32 s31, s24, s31
	s_add_i32 s65, s76, s51
	v_add_u32_e32 v14, s65, v174
	s_lshl_b32 s66, s50, 2
	s_add_i32 s66, s66, s76
	v_lshl_add_u32 v0, v144, 2, s66
	v_add_u32_e32 v0, 0x10000, v0
	ds_read_b128 v[96:99], v0
	ds_read_b128 v[100:103], v0 offset:32
	ds_read_b128 v[80:83], v0 offset:128
	ds_read_b128 v[84:87], v0 offset:160
	ds_read_b128 v[104:107], v0 offset:64
	ds_read_b128 v[108:111], v0 offset:96
	ds_read_b128 v[88:91], v0 offset:192
	ds_read_b128 v[92:95], v0 offset:224
	v_add_u32_e32 v15, v14, v175
	ds_read_b128 v[2:5], v15
	ds_read_b128 v[6:9], v15 offset:8192
	v_add_u32_e32 v15, v14, v176
	ds_read_b128 v[212:215], v15
	ds_read_b128 v[216:219], v15 offset:8192
	s_waitcnt lgkmcnt(3)
	v_mfma_f32_32x32x16_bf16 v[96:111], v[2:5], v[112:115], v[96:111]
	v_add_u32_e32 v15, v14, v177
	ds_read_b128 v[220:223], v15
	s_waitcnt lgkmcnt(3)
	v_mfma_f32_32x32x16_bf16 v[80:95], v[6:9], v[112:115], v[80:95]
	ds_read_b128 v[224:227], v15 offset:8192
	s_add_i32 s33, s73, s77
	s_mov_b32 m0, s33
	s_nop 0
	global_load_lds_dwordx4 v163, s[28:29]
	s_waitcnt lgkmcnt(3)
	v_mfma_f32_32x32x16_bf16 v[96:111], v[212:215], v[116:119], v[96:111]
	v_add_u32_e32 v15, v14, v178
	ds_read_b128 v[228:231], v15
	s_waitcnt lgkmcnt(3)
	v_mfma_f32_32x32x16_bf16 v[80:95], v[216:219], v[116:119], v[80:95]
	ds_read_b128 v[232:235], v15 offset:8192
	s_add_i32 m0, s33, 0x400
	s_nop 0
	global_load_lds_dwordx4 v189, s[28:29]
	s_waitcnt lgkmcnt(3)
	v_mfma_f32_32x32x16_bf16 v[96:111], v[220:223], v[120:123], v[96:111]
	v_add_u32_e32 v15, v14, v179
	ds_read_b128 v[2:5], v15
	s_waitcnt lgkmcnt(3)
	v_mfma_f32_32x32x16_bf16 v[80:95], v[224:227], v[120:123], v[80:95]
	ds_read_b128 v[6:9], v15 offset:8192
	s_add_i32 m0, s33, 0x800
	s_nop 0
	global_load_lds_dwordx4 v190, s[28:29]
	s_waitcnt lgkmcnt(3)
	v_mfma_f32_32x32x16_bf16 v[96:111], v[228:231], v[124:127], v[96:111]
	v_add_u32_e32 v15, v14, v180
	ds_read_b128 v[212:215], v15
	s_waitcnt lgkmcnt(3)
	v_mfma_f32_32x32x16_bf16 v[80:95], v[232:235], v[124:127], v[80:95]
	ds_read_b128 v[216:219], v15 offset:8192
	s_add_i32 m0, s33, 0xc00
	s_nop 0
	global_load_lds_dwordx4 v191, s[28:29]
	s_waitcnt lgkmcnt(3)
	v_mfma_f32_32x32x16_bf16 v[96:111], v[2:5], v[128:131], v[96:111]
	v_add_u32_e32 v15, v14, v181
	ds_read_b128 v[220:223], v15
	s_waitcnt lgkmcnt(3)
	v_mfma_f32_32x32x16_bf16 v[80:95], v[6:9], v[128:131], v[80:95]
	ds_read_b128 v[224:227], v15 offset:8192
	s_add_i32 m0, s72, s77
	s_nop 0
	global_load_lds_dword v172, s[68:69]
	s_waitcnt lgkmcnt(3)
	v_mfma_f32_32x32x16_bf16 v[96:111], v[212:215], v[132:135], v[96:111]
	v_add_u32_e32 v15, v14, v182
	ds_read_b128 v[228:231], v15
	s_waitcnt lgkmcnt(3)
	v_mfma_f32_32x32x16_bf16 v[80:95], v[216:219], v[132:135], v[80:95]
	ds_read_b128 v[232:235], v15 offset:8192
	s_waitcnt lgkmcnt(0)
	s_waitcnt vmcnt(5)
	s_barrier
	v_mfma_f32_32x32x16_bf16 v[96:111], v[220:223], v[136:139], v[96:111]
	v_mfma_f32_32x32x16_bf16 v[80:95], v[224:227], v[136:139], v[80:95]
	v_mfma_f32_32x32x16_bf16 v[96:111], v[228:231], v[140:143], v[96:111]
	v_mfma_f32_32x32x16_bf16 v[80:95], v[232:235], v[140:143], v[80:95]
	s_add_i32 s29, s62, 0xc0000001
	s_cmp_gt_u32 s29, 0xc000005d
	s_cbranch_scc1 .Lfx_nomask_q
	s_nop 11
	v_add_u32_e32 v0, s62, v147
	v_subrev_u32_e32 v2, 30, v0
	v_cmp_gt_u32_e32 vcc, 2.0, v2
	v_add_u32_e32 v2, 0xbfffffc2, v0
	s_nop 3
	v_cndmask_b32_e32 v96, v187, v96, vcc
	v_cmp_lt_u32_e32 vcc, s17, v2
	v_subrev_u32_e32 v2, 31, v0
	s_nop 0
	v_cndmask_b32_e32 v80, v187, v80, vcc
	v_cmp_gt_u32_e32 vcc, 2.0, v2
	v_add_u32_e32 v2, 0xbfffffc1, v0
	s_nop 0
	v_cndmask_b32_e32 v97, v187, v97, vcc
	v_cmp_lt_u32_e32 vcc, s17, v2
	v_subrev_u32_e32 v2, 32, v0
	s_nop 0
	v_cndmask_b32_e32 v81, v187, v81, vcc
	v_cmp_gt_u32_e32 vcc, 2.0, v2
	v_add_u32_e32 v2, 0xbfffffc0, v0
	s_nop 0
	v_cndmask_b32_e32 v98, v187, v98, vcc
	v_cmp_lt_u32_e32 vcc, s17, v2
	v_subrev_u32_e32 v2, 33, v0
	s_nop 0
	v_cndmask_b32_e32 v82, v187, v82, vcc
	v_cmp_gt_u32_e32 vcc, 2.0, v2
	v_add_u32_e32 v2, 0xbfffffbf, v0
	s_nop 0
	v_cndmask_b32_e32 v99, v187, v99, vcc
	v_cmp_lt_u32_e32 vcc, s17, v2
	v_subrev_u32_e32 v2, 38, v0
	s_nop 0
	v_cndmask_b32_e32 v83, v187, v83, vcc
	v_cmp_gt_u32_e32 vcc, 2.0, v2
	v_add_u32_e32 v2, 0xbfffffba, v0
	s_nop 0
	v_cndmask_b32_e32 v100, v187, v100, vcc
	v_cmp_lt_u32_e32 vcc, s17, v2
	v_subrev_u32_e32 v2, 39, v0
	s_nop 0
	v_cndmask_b32_e32 v84, v187, v84, vcc
	v_cmp_gt_u32_e32 vcc, 2.0, v2
	v_add_u32_e32 v2, 0xbfffffb9, v0
	s_nop 0
	v_cndmask_b32_e32 v101, v187, v101, vcc
	v_cmp_lt_u32_e32 vcc, s17, v2
	v_subrev_u32_e32 v2, 40, v0
	s_nop 0
	v_cndmask_b32_e32 v85, v187, v85, vcc
	v_cmp_gt_u32_e32 vcc, 2.0, v2
	v_add_u32_e32 v2, 0xbfffffb8, v0
	s_nop 0
	v_cndmask_b32_e32 v102, v187, v102, vcc
	v_cmp_lt_u32_e32 vcc, s17, v2
	v_subrev_u32_e32 v2, 41, v0
	s_nop 0
	v_cndmask_b32_e32 v86, v187, v86, vcc
	v_cmp_gt_u32_e32 vcc, 2.0, v2
	v_add_u32_e32 v2, 0xbfffffb7, v0
	s_nop 0
	v_cndmask_b32_e32 v103, v187, v103, vcc
	v_cmp_lt_u32_e32 vcc, s17, v2
	v_subrev_u32_e32 v2, 46, v0
	s_nop 0
	v_cndmask_b32_e32 v87, v187, v87, vcc
	v_cmp_gt_u32_e32 vcc, 2.0, v2
	v_add_u32_e32 v2, 0xbfffffb2, v0
	s_nop 0
	v_cndmask_b32_e32 v104, v187, v104, vcc
	v_cmp_lt_u32_e32 vcc, s17, v2
	v_subrev_u32_e32 v2, 47, v0
	s_nop 0
	v_cndmask_b32_e32 v88, v187, v88, vcc
	v_cmp_gt_u32_e32 vcc, 2.0, v2
	v_add_u32_e32 v2, 0xbfffffb1, v0
	s_nop 0
	v_cndmask_b32_e32 v105, v187, v105, vcc
	v_cmp_lt_u32_e32 vcc, s17, v2
	v_subrev_u32_e32 v2, 48, v0
	s_nop 0
	v_cndmask_b32_e32 v89, v187, v89, vcc
	v_cmp_gt_u32_e32 vcc, 2.0, v2
	v_add_u32_e32 v2, 0xbfffffb0, v0
	s_nop 0
	v_cndmask_b32_e32 v106, v187, v106, vcc
	v_cmp_lt_u32_e32 vcc, s17, v2
	v_subrev_u32_e32 v2, 49, v0
	s_nop 0
	v_cndmask_b32_e32 v90, v187, v90, vcc
	v_cmp_gt_u32_e32 vcc, 2.0, v2
	v_add_u32_e32 v2, 0xbfffffaf, v0
	s_nop 0
	v_cndmask_b32_e32 v107, v187, v107, vcc
	v_cmp_lt_u32_e32 vcc, s17, v2
	v_subrev_u32_e32 v2, 54, v0
	s_nop 0
	v_cndmask_b32_e32 v91, v187, v91, vcc
	v_cmp_gt_u32_e32 vcc, 2.0, v2
	v_add_u32_e32 v2, 0xbfffffaa, v0
	s_nop 0
	v_cndmask_b32_e32 v108, v187, v108, vcc
	v_cmp_lt_u32_e32 vcc, s17, v2
	v_subrev_u32_e32 v2, 55, v0
	s_nop 0
	v_cndmask_b32_e32 v92, v187, v92, vcc
	v_cmp_gt_u32_e32 vcc, 2.0, v2
	v_add_u32_e32 v2, 0xbfffffa9, v0
	s_nop 0
	v_cndmask_b32_e32 v109, v187, v109, vcc
	v_cmp_lt_u32_e32 vcc, s17, v2
	v_subrev_u32_e32 v2, 56, v0
	s_nop 0
	v_cndmask_b32_e32 v93, v187, v93, vcc
	v_cmp_gt_u32_e32 vcc, 2.0, v2
	v_add_u32_e32 v2, 0xbfffffa8, v0
	s_nop 0
	v_cndmask_b32_e32 v110, v187, v110, vcc
	v_cmp_lt_u32_e32 vcc, s17, v2
	v_subrev_u32_e32 v2, 57, v0
	v_add_u32_e32 v0, 0xbfffffa7, v0
	v_cndmask_b32_e32 v94, v187, v94, vcc
	v_cmp_gt_u32_e32 vcc, 2.0, v2
	s_nop 1
	v_cndmask_b32_e32 v111, v187, v111, vcc
	v_cmp_lt_u32_e32 vcc, s17, v0
	s_nop 1
	v_cndmask_b32_e32 v95, v187, v95, vcc

.Lfx_h1_done:
	s_lshl_b32 s64, s41, 7
	s_add_i32 s66, s64, 0xffffff80
	s_max_i32 s66, s66, 0
	s_mov_b32 s67, 0
	s_lshl_b64 s[28:29], s[66:67], 8
	s_add_u32 s28, s27, s28
	s_addc_u32 s29, s38, s29
	s_lshl_b64 s[68:69], s[66:67], 2
	s_add_u32 s68, s70, s68
	s_addc_u32 s69, s71, s69
	s_lshl_b64 s[30:31], s[66:67], 8
	s_add_u32 s30, s23, s30
	s_addc_u32 s31, s24, s31
	s_barrier
.Lfx_h1_joined:
	s_andn2_b64 vcc, exec, s[78:79]
	s_cbranch_vccnz .Lfx_h2_invis
	s_add_i32 m0, s74, s77
	s_nop 0
	global_load_lds_dwordx4 v188, s[30:31]
	v_max3_f32 v0, v96, v97, v80
	v_max3_f32 v2, v98, v99, v81
	v_max3_f32 v0, v0, v82, v83
	v_max3_f32 v2, v2, v102, v103
	v_max3_f32 v0, v0, v100, v101
	v_max3_f32 v2, v2, v86, v87
	v_max3_f32 v0, v0, v84, v85
	v_max3_f32 v2, v2, v106, v107
	v_max3_f32 v0, v0, v104, v105
	v_max3_f32 v2, v2, v90, v91
	v_max3_f32 v0, v0, v88, v89
	v_max3_f32 v2, v2, v110, v111
	v_max3_f32 v0, v0, v108, v109
	v_max3_f32 v2, v2, v94, v95
	v_max3_f32 v0, v0, v92, v93
	v_max_f32_e32 v2, v2, v2
	v_max_f32_e32 v0, v0, v0
	v_max_f32_e32 v0, v0, v2
	v_mov_b32_e32 v2, v0
	s_nop 1
	v_permlane32_swap_b32_e32 v0, v2
	v_max_f32_e32 v2, v2, v2
	v_max_f32_e32 v0, v0, v0
	v_max_f32_e32 v0, v0, v2
	v_add_f32_e32 v2, 0x41000000, v192
	v_cmp_gt_f32_e32 vcc, v0, v2
	s_cbranch_vccz .Lfx_sm_exp_v
	v_max_f32_e32 v0, v0, v0
	v_max_f32_e32 v2, v192, v192
	v_max_f32_e32 v2, v2, v0
	v_sub_f32_e32 v0, v192, v2
	v_exp_f32_e32 v0, v0
	v_mov_b32_e32 v192, v2
	v_mul_f32_e32 v162, v162, v0
	v_pk_mul_f32 v[78:79], v[78:79], v[0:1] op_sel_hi:[1,0]
	v_pk_mul_f32 v[76:77], v[76:77], v[0:1] op_sel_hi:[1,0]
	v_pk_mul_f32 v[74:75], v[74:75], v[0:1] op_sel_hi:[1,0]
	v_pk_mul_f32 v[72:73], v[72:73], v[0:1] op_sel_hi:[1,0]
	v_pk_mul_f32 v[70:71], v[70:71], v[0:1] op_sel_hi:[1,0]
	v_pk_mul_f32 v[68:69], v[68:69], v[0:1] op_sel_hi:[1,0]
	v_pk_mul_f32 v[66:67], v[66:67], v[0:1] op_sel_hi:[1,0]
	v_pk_mul_f32 v[64:65], v[64:65], v[0:1] op_sel_hi:[1,0]
	v_pk_mul_f32 v[62:63], v[62:63], v[0:1] op_sel_hi:[1,0]
	v_pk_mul_f32 v[60:61], v[60:61], v[0:1] op_sel_hi:[1,0]
	v_pk_mul_f32 v[58:59], v[58:59], v[0:1] op_sel_hi:[1,0]
	v_pk_mul_f32 v[56:57], v[56:57], v[0:1] op_sel_hi:[1,0]
	v_pk_mul_f32 v[54:55], v[54:55], v[0:1] op_sel_hi:[1,0]
	v_pk_mul_f32 v[52:53], v[52:53], v[0:1] op_sel_hi:[1,0]
	v_pk_mul_f32 v[50:51], v[50:51], v[0:1] op_sel_hi:[1,0]
	v_pk_mul_f32 v[48:49], v[48:49], v[0:1] op_sel_hi:[1,0]
	v_pk_mul_f32 v[46:47], v[46:47], v[0:1] op_sel_hi:[1,0]
	v_pk_mul_f32 v[44:45], v[44:45], v[0:1] op_sel_hi:[1,0]
	v_pk_mul_f32 v[42:43], v[42:43], v[0:1] op_sel_hi:[1,0]
	v_pk_mul_f32 v[40:41], v[40:41], v[0:1] op_sel_hi:[1,0]
	v_pk_mul_f32 v[38:39], v[38:39], v[0:1] op_sel_hi:[1,0]
	v_pk_mul_f32 v[36:37], v[36:37], v[0:1] op_sel_hi:[1,0]
	v_pk_mul_f32 v[34:35], v[34:35], v[0:1] op_sel_hi:[1,0]
	v_pk_mul_f32 v[32:33], v[32:33], v[0:1] op_sel_hi:[1,0]
	v_pk_mul_f32 v[30:31], v[30:31], v[0:1] op_sel_hi:[1,0]
	v_pk_mul_f32 v[28:29], v[28:29], v[0:1] op_sel_hi:[1,0]
	v_pk_mul_f32 v[26:27], v[26:27], v[0:1] op_sel_hi:[1,0]
	v_pk_mul_f32 v[24:25], v[24:25], v[0:1] op_sel_hi:[1,0]
	v_pk_mul_f32 v[22:23], v[22:23], v[0:1] op_sel_hi:[1,0]
	v_pk_mul_f32 v[20:21], v[20:21], v[0:1] op_sel_hi:[1,0]
	v_pk_mul_f32 v[18:19], v[18:19], v[0:1] op_sel_hi:[1,0]
	v_pk_mul_f32 v[16:17], v[16:17], v[0:1] op_sel_hi:[1,0]
.Lfx_sm_exp_v:
	v_sub_f32_e32 v0, v96, v192
	v_exp_f32_e32 v193, v0
	v_sub_f32_e32 v0, v80, v192
	v_exp_f32_e32 v194, v0
	v_sub_f32_e32 v0, v97, v192
	global_load_lds_dwordx4 v188, s[30:31] offset:1024
	v_exp_f32_e32 v2, v0
	v_sub_f32_e32 v0, v81, v192
	v_exp_f32_e32 v0, v0
	v_add_f32_e32 v3, v193, v194
	v_add_f32_e32 v4, v2, v0
	v_add_f32_e32 v5, v3, v1
	s_nop 0
	v_add_f32_e32 v9, v4, v5
	v_sub_f32_e32 v3, v98, v192
	v_sub_f32_e32 v4, v82, v192
	v_exp_f32_e32 v3, v3
	v_exp_f32_e32 v98, v4
	v_sub_f32_e32 v4, v99, v192
	v_sub_f32_e32 v5, v83, v192
	v_exp_f32_e32 v4, v4
	v_exp_f32_e32 v8, v5
	v_add_f32_e32 v5, v3, v98
	v_cvt_pk_bf16_f32 v196, v193, v2
	v_cvt_pk_bf16_f32 v197, v3, v4
	v_add_f32_e32 v6, v4, v8
	v_add_f32_e32 v7, v5, v9
	v_sub_f32_e32 v5, v100, v192
	v_add_f32_e32 v11, v6, v7
	v_sub_f32_e32 v6, v84, v192
	v_exp_f32_e32 v5, v5
	v_exp_f32_e32 v9, v6
	v_sub_f32_e32 v6, v101, v192
	v_sub_f32_e32 v7, v85, v192
	v_exp_f32_e32 v6, v6
	v_exp_f32_e32 v10, v7
	global_load_lds_dwordx4 v188, s[30:31] offset:2048
	v_add_f32_e32 v7, v5, v9
	v_cvt_pk_bf16_f32 v198, v5, v6
	v_add_f32_e32 v12, v6, v10
	v_add_f32_e32 v13, v7, v11
	v_sub_f32_e32 v7, v102, v192
	v_add_f32_e32 v13, v12, v13
	v_sub_f32_e32 v11, v86, v192
	v_sub_f32_e32 v12, v103, v192
	v_exp_f32_e32 v7, v7
	v_exp_f32_e32 v11, v11
	v_exp_f32_e32 v14, v12
	v_sub_f32_e32 v12, v87, v192
	v_exp_f32_e32 v12, v12
	v_add_f32_e32 v15, v7, v11
	v_cvt_pk_bf16_f32 v199, v7, v14
	v_cvt_pk_bf16_f32 v200, v194, v0
	v_add_f32_e32 v80, v14, v12
	v_add_f32_e32 v81, v15, v13
	v_sub_f32_e32 v13, v104, v192
	v_add_f32_e32 v81, v80, v81
	v_sub_f32_e32 v15, v88, v192
	v_sub_f32_e32 v80, v105, v192
	v_exp_f32_e32 v13, v13
	v_exp_f32_e32 v15, v15
	v_exp_f32_e32 v82, v80
	v_sub_f32_e32 v80, v89, v192
	v_exp_f32_e32 v80, v80
	v_add_f32_e32 v83, v13, v15
	v_cvt_pk_bf16_f32 v201, v98, v8
	v_cvt_pk_bf16_f32 v202, v9, v10
	global_load_lds_dwordx4 v188, s[30:31] offset:3072
	v_add_f32_e32 v84, v82, v80
	v_add_f32_e32 v85, v83, v81
	v_sub_f32_e32 v81, v106, v192
	v_add_f32_e32 v85, v84, v85
	v_sub_f32_e32 v83, v90, v192
	v_sub_f32_e32 v84, v107, v192
	v_exp_f32_e32 v81, v81
	v_exp_f32_e32 v83, v83
	v_exp_f32_e32 v86, v84
	v_sub_f32_e32 v84, v91, v192
	v_exp_f32_e32 v84, v84
	v_add_f32_e32 v87, v81, v83
	v_cvt_pk_bf16_f32 v203, v11, v12
	v_cvt_pk_bf16_f32 v204, v13, v82
	v_add_f32_e32 v88, v86, v84
	v_add_f32_e32 v89, v87, v85
	v_sub_f32_e32 v85, v108, v192
	v_add_f32_e32 v89, v88, v89
	v_sub_f32_e32 v87, v92, v192
	v_sub_f32_e32 v88, v109, v192
	v_exp_f32_e32 v85, v85
	v_exp_f32_e32 v87, v87
	v_exp_f32_e32 v90, v88
	s_add_i32 s64, s76, s51
	v_add_u32_e32 v10, s64, v183
	ds_read_b64_tr_b16 v[2:3], v10 offset:32768
	ds_read_b64_tr_b16 v[4:5], v10 offset:34816
	ds_read_b64_tr_b16 v[6:7], v10 offset:36864
	ds_read_b64_tr_b16 v[8:9], v10 offset:38912
	ds_read_b64_tr_b16 v[212:213], v10 offset:40960
	ds_read_b64_tr_b16 v[214:215], v10 offset:43008
	ds_read_b64_tr_b16 v[216:217], v10 offset:45056
	ds_read_b64_tr_b16 v[218:219], v10 offset:47104
	v_sub_f32_e32 v88, v93, v192
	v_exp_f32_e32 v88, v88
	v_add_f32_e32 v91, v85, v87
	v_cvt_pk_bf16_f32 v205, v81, v86
	v_cvt_pk_bf16_f32 v206, v85, v90
	v_add_f32_e32 v92, v90, v88
	v_add_f32_e32 v93, v91, v89
	v_sub_f32_e32 v89, v110, v192
	v_add_f32_e32 v93, v92, v93
	v_sub_f32_e32 v91, v94, v192
	v_sub_f32_e32 v92, v111, v192
	v_exp_f32_e32 v89, v89
	v_exp_f32_e32 v91, v91
	v_exp_f32_e32 v94, v92
	v_sub_f32_e32 v92, v95, v192
	v_exp_f32_e32 v92, v92
	v_add_f32_e32 v95, v89, v91
	v_cvt_pk_bf16_f32 v207, v89, v94
	v_cvt_pk_bf16_f32 v208, v15, v80
	v_add_f32_e32 v96, v94, v92
	v_add_f32_e32 v97, v95, v93
	v_cvt_pk_bf16_f32 v209, v83, v84
	v_add_f32_e32 v93, v96, v97
	v_add_f32_e32 v162, v162, v93
	v_cvt_pk_bf16_f32 v210, v87, v88
	v_cvt_pk_bf16_f32 v211, v91, v92
	s_waitcnt vmcnt(4)
	s_branch .Lfx_h2_done
.Lfx_h2_invis:
	s_add_i32 m0, s74, s77
	s_nop 0
	global_load_lds_dwordx4 v188, s[30:31]
	global_load_lds_dwordx4 v188, s[30:31] offset:1024
	global_load_lds_dwordx4 v188, s[30:31] offset:2048
	global_load_lds_dwordx4 v188, s[30:31] offset:3072
	s_waitcnt vmcnt(4)
